# v41 + norm-phase row sums as DPP adds (row_shr 1/2/4/8, row_bcast 15/31) instead of six ds_bpermute round trips
# baseline (speedup 1.0000x reference)
; #define GAS __attribute__((address_space(1)))
; __device__ __forceinline__ unsigned pk2(float lo, float hi) { return f2bf(lo) | (f2bf(hi) << 16); }
; __device__ __forceinline__ float lane_read(float v, int src_lane) { return __builtin_bit_cast(float, __builtin_amdgcn_ds_bpermute(src_lane << 2, __builtin_bit_cast(int, v))); }
; __device__ __forceinline__ float wave_sum(float v, int lane) {
; #pragma unroll
;     for (int o = 1; o < 64; o <<= 1) v += lane_read(v, lane ^ o);
;     return v;
; }
;     ...
;     for (int row = row_lo + gw; row < nrows; row += NGW) {
;         const int s = row < SEQ ? 0 : row < ML ? 1 : 2;
;         const GAS float* shp = MOD + (size_t)s * (NMOD * DM) + (which ? 3 : 0) * DM; const GAS float* scp = shp + DM;
;         f32x4 v[8]; float ss = 0.f;
; #pragma unroll
;         for (int j = 0; j < 8; ++j) v[j] = nv[j];
;         { const int nrow = row + NGW; if (nrow < nrows) { const GAS float* xn = nrow < ML ? xl + (size_t)nrow * DM : xc + (size_t)(nrow - ML) * DM;
; #pragma unroll
;             for (int j = 0; j < 8; ++j) nv[j] = *(const GAS f32x4*)(xn + 4 * (F.lane + 64 * j)); } }
;         __builtin_amdgcn_sched_barrier(0);
;         if (row >= ML && nslab > 0) {
;             const GAS float* sl = WSP(float, WS_SLAB) + (size_t)(row - ML) * DM; GAS float* xw = WSP(float, WS_XC) + (size_t)(row - ML) * DM;
;             for (int ks = 0; ks < nslab; ++ks)
; #pragma unroll
;                 for (int j = 0; j < 8; ++j) v[j] += *(const GAS f32x4*)(sl + (size_t)ks * MC * DM + 4 * (F.lane + 64 * j));
; #pragma unroll
;             for (int j = 0; j < 8; ++j) *(GAS f32x4*)(xw + 4 * (F.lane + 64 * j)) = v[j];
;         }
; #pragma unroll
;         for (int j = 0; j < 8; ++j) ss += (v[j].x * v[j].x + v[j].y * v[j].y) + (v[j].z * v[j].z + v[j].w * v[j].w);
;         const float rstd = 1.0f / sqrtf(wave_sum(ss, F.lane) * (1.0f / DM) + EPS);
;         GAS bf16* hr = H + (size_t)row * DM;
; #pragma unroll
;         for (int j = 0; j < 8; ++j) { const int k = 4 * (F.lane + 64 * j);
;             const f32x4 g = *(const GAS f32x4*)(gain + k), sc = *(const GAS f32x4*)(scp + k), sh = *(const GAS f32x4*)(shp + k);
;             const f32x4 y = (v[j] * rstd * g) * (1.0f + sc) + sh;
;             v2u o; o.x = pk2(y.x, y.y); o.y = pk2(y.z, y.w); *(GAS v2u*)(hr + k) = o; }
.LBB0_148:
	v_pk_mul_f32 v[104:105], v[60:61], v[60:61]
	v_pk_mul_f32 v[106:107], v[56:57], v[56:57]
	v_pk_mul_f32 v[100:101], v[62:63], v[62:63]
	v_pk_mul_f32 v[102:103], v[58:59], v[58:59]
	v_mov_b32_e32 v108, v104
	v_mov_b32_e32 v109, v106
	v_mov_b32_e32 v106, v105
	v_pk_mul_f32 v[96:97], v[54:55], v[54:55]
	v_pk_mul_f32 v[98:99], v[52:53], v[52:53]
	v_pk_add_f32 v[104:105], v[108:109], v[106:107]
	v_mov_b32_e32 v106, v100
	v_mov_b32_e32 v107, v102
	v_mov_b32_e32 v102, v101
	v_pk_add_f32 v[100:101], v[106:107], v[102:103]
	v_pk_mov_b32 v[102:103], v[98:99], v[96:97] op_sel:[1,0]
	v_mov_b32_e32 v99, v97
	v_pk_add_f32 v[96:97], v[102:103], v[98:99]
	v_pk_add_f32 v[100:101], v[104:105], v[100:101]
	v_pk_add_f32 v[96:97], v[96:97], v[96:97] op_sel_hi:[0,1]
	v_mul_f32_e32 v96, v44, v44
	v_pk_fma_f32 v[98:99], v[44:45], v[44:45], v[96:97] op_sel_hi:[1,1,0]
	v_mul_f32_e32 v96, v46, v46
	v_pk_add_f32 v[100:101], v[100:101], v[100:101] op_sel_hi:[0,1]
	v_pk_fma_f32 v[102:103], v[46:47], v[46:47], v[96:97] op_sel_hi:[1,1,0]
	v_mul_f32_e32 v98, v40, v40
	v_mul_f32_e32 v102, v41, v41
	v_mul_f32_e32 v96, v42, v42
	v_mul_f32_e32 v100, v43, v43
	v_pk_mul_f32 v[76:77], v[38:39], v[38:39]
	v_pk_mul_f32 v[94:95], v[36:37], v[36:37]
	v_pk_add_f32 v[98:99], v[98:99], v[102:103]
	v_pk_add_f32 v[96:97], v[96:97], v[100:101]
	s_cmp_lt_i32 s12, 0x8000
	s_movk_i32 s4, 0x3000
	v_pk_add_f32 v[96:97], v[98:99], v[96:97]
	v_pk_mov_b32 v[98:99], v[94:95], v[76:77] op_sel:[1,0]
	v_mov_b32_e32 v95, v77
	s_cselect_b32 s4, s4, 0x6000
	s_cmpk_gt_i32 s12, 0x3fff
	v_pk_add_f32 v[76:77], v[98:99], v[94:95]
	s_cselect_b32 s4, s4, 0
	v_pk_add_f32 v[76:77], v[76:77], v[76:77] op_sel_hi:[0,1]
	s_lshl_b32 s4, s4, 2
	v_mul_f32_e32 v76, v32, v32
	s_add_u32 s10, s2, s4
	v_pk_fma_f32 v[94:95], v[32:33], v[32:33], v[76:77] op_sel_hi:[1,1,0]
	v_mul_f32_e32 v76, v34, v34
	s_addc_u32 s11, s3, 0
	v_pk_add_f32 v[96:97], v[96:97], v[96:97] op_sel_hi:[0,1]
	v_pk_fma_f32 v[98:99], v[34:35], v[34:35], v[76:77] op_sel_hi:[1,1,0]
	s_add_u32 s12, s10, 0x2000
	v_mul_f32_e32 v94, v48, v48
	v_mul_f32_e32 v98, v49, v49
	v_mul_f32_e32 v76, v50, v50
	v_mul_f32_e32 v96, v51, v51
	s_addc_u32 s13, s11, 0
	v_pk_add_f32 v[98:99], v[94:95], v[98:99]
	v_pk_add_f32 v[76:77], v[76:77], v[96:97]
	global_load_dwordx4 v[94:97], v[64:65], off
	v_pk_add_f32 v[76:77], v[98:99], v[76:77]
	global_load_dwordx4 v[98:101], v85, s[12:13]
	global_load_dwordx4 v[102:105], v85, s[10:11]
	v_add_f32_e32 v76, v76, v77
	s_nop 1
	s_mov_b32 s50, s20
	v_readlane_b32 s20, v255, 22
	v_readlane_b32 s21, v255, 23
	s_add_u32 s18, s18, s20
	v_add_f32_dpp v76, v76, v76 row_shr:1 row_mask:0xf bank_mask:0xf bound_ctrl:0
	s_nop 1
	s_addc_u32 s19, s19, s21
	v_add_f32_dpp v76, v76, v76 row_shr:2 row_mask:0xf bank_mask:0xf bound_ctrl:0
	s_nop 1
	v_add_f32_dpp v76, v76, v76 row_shr:4 row_mask:0xf bank_mask:0xf bound_ctrl:0
	s_nop 1
	v_add_f32_dpp v76, v76, v76 row_shr:8 row_mask:0xf bank_mask:0xf bound_ctrl:0
	s_nop 1
	v_add_f32_dpp v76, v76, v76 row_bcast:15 row_mask:0xa bank_mask:0xf
	s_nop 1
	v_add_f32_dpp v76, v76, v76 row_bcast:31 row_mask:0xc bank_mask:0xf
	s_nop 0
	v_readlane_b32 s4, v76, 63
	s_nop 1
	v_mov_b32_e32 v76, s4
	v_fmamk_f32 v76, v76, 0x3a000000, v212
	v_mul_f32_e32 v77, 0x4f800000, v76
	v_cmp_gt_f32_e32 vcc, s60, v76
	s_nop 1
	v_cndmask_b32_e32 v76, v76, v77, vcc
	v_sqrt_f32_e32 v77, v76
	s_nop 0
	v_add_u32_e32 v93, -1, v77
	v_fma_f32 v106, -v93, v77, v76
	v_cmp_ge_f32_e64 s[4:5], 0, v106
	v_add_u32_e32 v106, 1, v77
	s_nop 0
	v_cndmask_b32_e64 v93, v77, v93, s[4:5]
	v_fma_f32 v77, -v106, v77, v76
	v_cmp_lt_f32_e64 s[4:5], 0, v77
	s_nop 1
	v_cndmask_b32_e64 v77, v93, v106, s[4:5]
	v_mul_f32_e32 v93, 0x37800000, v77
	v_cndmask_b32_e32 v77, v77, v93, vcc
	v_cmp_class_f32_e32 vcc, v76, v213
	s_nop 1
	v_cndmask_b32_e32 v76, v77, v76, vcc
	v_div_scale_f32 v77, s[4:5], v76, v76, 1.0
	v_rcp_f32_e32 v93, v77
	v_readlane_b32 s4, v255, 24
	v_readlane_b32 s5, v255, 25
	v_fma_f32 v106, -v77, v93, 1.0
	v_fmac_f32_e32 v93, v106, v93
	v_div_scale_f32 v106, vcc, 1.0, v76, 1.0
	v_mul_f32_e32 v107, v106, v93
	v_fma_f32 v108, -v77, v107, v106
	v_fmac_f32_e32 v107, v108, v93
	v_fma_f32 v77, -v77, v107, v106
	v_div_fmas_f32 v77, v77, v93, v107
	v_div_fixup_f32 v76, v77, v76, 1.0
	v_pk_mul_f32 v[62:63], v[62:63], v[76:77] op_sel_hi:[1,0]
	v_pk_mul_f32 v[60:61], v[60:61], v[76:77] op_sel_hi:[1,0]
	s_waitcnt vmcnt(2)
	v_pk_mul_f32 v[62:63], v[96:97], v[62:63]
	v_pk_mul_f32 v[60:61], v[94:95], v[60:61]
	s_waitcnt vmcnt(1)
	v_pk_add_f32 v[96:97], v[98:99], 1.0 op_sel_hi:[1,0]
	v_pk_add_f32 v[94:95], v[100:101], 1.0 op_sel_hi:[1,0]
	s_waitcnt vmcnt(0)
	v_pk_fma_f32 v[60:61], v[96:97], v[60:61], v[102:103]
	v_pk_fma_f32 v[62:63], v[94:95], v[62:63], v[104:105]
	v_bfe_u32 v77, v60, 16, 1
	v_add3_u32 v60, v60, v77, s61
	v_bfe_u32 v77, v61, 16, 1
	v_lshrrev_b32_e32 v60, 16, v60
	v_add3_u32 v61, v61, v77, s61
	v_and_or_b32 v60, v61, s86, v60
	v_bfe_u32 v61, v62, 16, 1
	v_add3_u32 v61, v62, v61, s61
	v_bfe_u32 v62, v63, 16, 1
	v_lshrrev_b32_e32 v61, 16, v61
	v_add3_u32 v62, v63, v62, s61
	v_and_or_b32 v61, v62, s86, v61
	global_store_dwordx2 v[74:75], v[60:61], off
	global_load_dwordx4 v[60:63], v[64:65], off offset:1024
	s_nop 0
	global_load_dwordx4 v[94:97], v86, s[12:13]
	global_load_dwordx4 v[98:101], v85, s[10:11] offset:1024
	v_pk_mul_f32 v[58:59], v[58:59], v[76:77] op_sel_hi:[1,0]
	v_pk_mul_f32 v[56:57], v[56:57], v[76:77] op_sel_hi:[1,0]
	v_pk_mul_f32 v[54:55], v[54:55], v[76:77] op_sel_hi:[1,0]
	v_pk_mul_f32 v[52:53], v[52:53], v[76:77] op_sel_hi:[1,0]
	v_pk_mul_f32 v[46:47], v[46:47], v[76:77] op_sel_hi:[1,0]
	v_pk_mul_f32 v[44:45], v[44:45], v[76:77] op_sel_hi:[1,0]
	v_pk_mul_f32 v[42:43], v[42:43], v[76:77] op_sel_hi:[1,0]
	v_pk_mul_f32 v[40:41], v[40:41], v[76:77] op_sel_hi:[1,0]
	v_pk_mul_f32 v[38:39], v[38:39], v[76:77] op_sel_hi:[1,0]
	v_pk_mul_f32 v[36:37], v[36:37], v[76:77] op_sel_hi:[1,0]
	v_pk_mul_f32 v[34:35], v[34:35], v[76:77] op_sel_hi:[1,0]
	v_pk_mul_f32 v[32:33], v[32:33], v[76:77] op_sel_hi:[1,0]
	v_pk_mul_f32 v[102:103], v[50:51], v[76:77] op_sel_hi:[1,0]
	v_pk_mul_f32 v[76:77], v[48:49], v[76:77] op_sel_hi:[1,0]
	v_mov_b64_e32 v[50:51], v[2:3]
	s_andn2_b64 vcc, exec, s[8:9]
	v_mov_b64_e32 v[48:49], v[0:1]
	s_waitcnt vmcnt(2)
; #define GAS __attribute__((address_space(1)))
; __device__ __forceinline__ unsigned f2bf(float f) { unsigned u = __builtin_bit_cast(unsigned, f); return (u + 0x7fffu + ((u >> 16) & 1u)) >> 16; }
; __device__ __forceinline__ unsigned pk2(float lo, float hi) { return f2bf(lo) | (f2bf(hi) << 16); }
;     ...
;         GAS bf16* hr = H + (size_t)row * DM;
; #pragma unroll
;         for (int j = 0; j < 8; ++j) { const int k = 4 * (F.lane + 64 * j);
;             const f32x4 g = *(const GAS f32x4*)(gain + k), sc = *(const GAS f32x4*)(scp + k), sh = *(const GAS f32x4*)(shp + k);
;             const f32x4 y = (v[j] * rstd * g) * (1.0f + sc) + sh;
;             v2u o; o.x = pk2(y.x, y.y); o.y = pk2(y.z, y.w); *(GAS v2u*)(hr + k) = o; }
	v_pk_mul_f32 v[56:57], v[60:61], v[56:57]
	v_pk_mul_f32 v[58:59], v[62:63], v[58:59]
	s_waitcnt vmcnt(1)
	v_pk_add_f32 v[60:61], v[96:97], 1.0 op_sel_hi:[1,0]
	v_pk_add_f32 v[62:63], v[94:95], 1.0 op_sel_hi:[1,0]
	s_waitcnt vmcnt(0)
	v_pk_fma_f32 v[58:59], v[60:61], v[58:59], v[100:101]
	v_pk_fma_f32 v[56:57], v[62:63], v[56:57], v[98:99]
	v_bfe_u32 v62, v58, 16, 1
	v_bfe_u32 v60, v56, 16, 1
	v_bfe_u32 v61, v57, 16, 1
	v_bfe_u32 v63, v59, 16, 1
	v_add3_u32 v56, v56, v60, s61
	v_add3_u32 v58, v58, v62, s61
	v_add3_u32 v57, v57, v61, s61
	v_add3_u32 v59, v59, v63, s61
	v_lshrrev_b32_e32 v56, 16, v56
	v_lshrrev_b32_e32 v58, 16, v58
	v_and_or_b32 v56, v57, s86, v56
	v_and_or_b32 v57, v59, s86, v58
	global_store_dwordx2 v[74:75], v[56:57], off offset:512
	global_load_dwordx4 v[56:59], v[64:65], off offset:2048
	s_nop 0
	global_load_dwordx4 v[60:63], v87, s[12:13]
	global_load_dwordx4 v[94:97], v85, s[10:11] offset:2048
	s_waitcnt vmcnt(2)
	v_pk_mul_f32 v[52:53], v[56:57], v[52:53]
	v_pk_mul_f32 v[54:55], v[58:59], v[54:55]
	s_waitcnt vmcnt(1)
	v_pk_add_f32 v[56:57], v[62:63], 1.0 op_sel_hi:[1,0]
	v_pk_add_f32 v[58:59], v[60:61], 1.0 op_sel_hi:[1,0]
	s_waitcnt vmcnt(0)
	v_pk_fma_f32 v[54:55], v[56:57], v[54:55], v[96:97]
	v_pk_fma_f32 v[52:53], v[58:59], v[52:53], v[94:95]
	v_bfe_u32 v58, v54, 16, 1
	v_bfe_u32 v56, v52, 16, 1
	v_bfe_u32 v57, v53, 16, 1
	v_bfe_u32 v59, v55, 16, 1
	v_add3_u32 v52, v52, v56, s61
	v_add3_u32 v54, v54, v58, s61
	v_add3_u32 v53, v53, v57, s61
	v_add3_u32 v55, v55, v59, s61
	v_lshrrev_b32_e32 v52, 16, v52
	v_lshrrev_b32_e32 v54, 16, v54
	v_and_or_b32 v52, v53, s86, v52
	v_and_or_b32 v53, v55, s86, v54
	global_store_dwordx2 v[74:75], v[52:53], off offset:1024
	global_load_dwordx4 v[52:55], v[64:65], off offset:3072
	s_nop 0
	global_load_dwordx4 v[56:59], v88, s[12:13]
	global_load_dwordx4 v[60:63], v85, s[10:11] offset:3072
	s_waitcnt vmcnt(2)
	v_pk_mul_f32 v[44:45], v[52:53], v[44:45]
	v_pk_mul_f32 v[46:47], v[54:55], v[46:47]
	s_waitcnt vmcnt(1)
	v_pk_add_f32 v[52:53], v[58:59], 1.0 op_sel_hi:[1,0]
	v_pk_add_f32 v[54:55], v[56:57], 1.0 op_sel_hi:[1,0]
	s_waitcnt vmcnt(0)
	v_pk_fma_f32 v[46:47], v[52:53], v[46:47], v[62:63]
	v_pk_fma_f32 v[44:45], v[54:55], v[44:45], v[60:61]
	v_bfe_u32 v54, v46, 16, 1
	v_bfe_u32 v52, v44, 16, 1
	v_bfe_u32 v53, v45, 16, 1
	v_bfe_u32 v55, v47, 16, 1
	v_add3_u32 v44, v44, v52, s61
	v_add3_u32 v46, v46, v54, s61
	v_add3_u32 v45, v45, v53, s61
	v_add3_u32 v47, v47, v55, s61
	v_lshrrev_b32_e32 v44, 16, v44
	v_lshrrev_b32_e32 v46, 16, v46
	v_and_or_b32 v44, v45, s86, v44
	v_and_or_b32 v45, v47, s86, v46
	global_store_dwordx2 v[74:75], v[44:45], off offset:1536
	global_load_dwordx4 v[44:47], v[66:67], off
	s_nop 0
	global_load_dwordx4 v[52:55], v89, s[12:13]
	global_load_dwordx4 v[56:59], v89, s[10:11]
	s_waitcnt vmcnt(2)
	v_pk_mul_f32 v[40:41], v[44:45], v[40:41]
	v_pk_mul_f32 v[42:43], v[46:47], v[42:43]
	s_waitcnt vmcnt(1)
	v_pk_add_f32 v[44:45], v[54:55], 1.0 op_sel_hi:[1,0]
	v_pk_add_f32 v[46:47], v[52:53], 1.0 op_sel_hi:[1,0]
	s_waitcnt vmcnt(0)
	v_pk_fma_f32 v[42:43], v[42:43], v[44:45], v[58:59]
	v_pk_fma_f32 v[40:41], v[40:41], v[46:47], v[56:57]
	v_bfe_u32 v46, v42, 16, 1
	v_bfe_u32 v44, v40, 16, 1
	v_bfe_u32 v45, v41, 16, 1
	v_bfe_u32 v47, v43, 16, 1
	v_add3_u32 v40, v40, v44, s61
	v_add3_u32 v42, v42, v46, s61
	v_add3_u32 v41, v41, v45, s61
	v_add3_u32 v43, v43, v47, s61
	v_lshrrev_b32_e32 v40, 16, v40
	v_lshrrev_b32_e32 v42, 16, v42
	v_and_or_b32 v40, v41, s86, v40
	v_and_or_b32 v41, v43, s86, v42
	global_store_dwordx2 v[74:75], v[40:41], off offset:2048
	global_load_dwordx4 v[40:43], v[68:69], off
	s_nop 0
	global_load_dwordx4 v[44:47], v90, s[12:13]
	global_load_dwordx4 v[52:55], v90, s[10:11]
	v_mov_b64_e32 v[58:59], v[26:27]
	v_mov_b64_e32 v[56:57], v[24:25]
	s_waitcnt vmcnt(2)
	v_pk_mul_f32 v[36:37], v[36:37], v[40:41]
	v_pk_mul_f32 v[38:39], v[38:39], v[42:43]
	s_waitcnt vmcnt(1)
	v_pk_add_f32 v[40:41], v[46:47], 1.0 op_sel_hi:[1,0]
	v_pk_add_f32 v[42:43], v[44:45], 1.0 op_sel_hi:[1,0]
	s_waitcnt vmcnt(0)
	v_pk_fma_f32 v[38:39], v[38:39], v[40:41], v[54:55]
	v_pk_fma_f32 v[36:37], v[36:37], v[42:43], v[52:53]
	v_bfe_u32 v42, v38, 16, 1
	v_bfe_u32 v40, v36, 16, 1
	v_bfe_u32 v41, v37, 16, 1
	v_bfe_u32 v43, v39, 16, 1
	v_add3_u32 v36, v36, v40, s61
	v_add3_u32 v38, v38, v42, s61
	v_add3_u32 v37, v37, v41, s61
	v_add3_u32 v39, v39, v43, s61
	v_lshrrev_b32_e32 v36, 16, v36
	v_lshrrev_b32_e32 v38, 16, v38
	v_and_or_b32 v36, v37, s86, v36
	v_and_or_b32 v37, v39, s86, v38
	global_store_dwordx2 v[74:75], v[36:37], off offset:2560
	global_load_dwordx4 v[36:39], v[70:71], off
	s_nop 0
	global_load_dwordx4 v[40:43], v91, s[12:13]
	global_load_dwordx4 v[44:47], v91, s[10:11]
	v_mov_b64_e32 v[54:55], v[22:23]
	v_mov_b64_e32 v[52:53], v[20:21]
	s_waitcnt vmcnt(2)
	v_pk_mul_f32 v[32:33], v[32:33], v[36:37]
	v_pk_mul_f32 v[34:35], v[34:35], v[38:39]
	s_waitcnt vmcnt(1)
	v_pk_add_f32 v[36:37], v[42:43], 1.0 op_sel_hi:[1,0]
	v_pk_add_f32 v[38:39], v[40:41], 1.0 op_sel_hi:[1,0]
	s_waitcnt vmcnt(0)
	v_pk_fma_f32 v[34:35], v[34:35], v[36:37], v[46:47]
	v_pk_fma_f32 v[32:33], v[32:33], v[38:39], v[44:45]
	v_bfe_u32 v38, v34, 16, 1
	v_bfe_u32 v36, v32, 16, 1
	v_bfe_u32 v37, v33, 16, 1
	v_bfe_u32 v39, v35, 16, 1
	v_add3_u32 v32, v32, v36, s61
	v_add3_u32 v34, v34, v38, s61
	v_add3_u32 v33, v33, v37, s61
	v_add3_u32 v35, v35, v39, s61
	v_lshrrev_b32_e32 v32, 16, v32
	v_lshrrev_b32_e32 v34, 16, v34
	v_and_or_b32 v32, v33, s86, v32
	v_and_or_b32 v33, v35, s86, v34
	global_store_dwordx2 v[74:75], v[32:33], off offset:3072
	global_load_dwordx4 v[60:63], v[72:73], off
	global_load_dwordx4 v[94:97], v92, s[12:13]
	global_load_dwordx4 v[98:101], v92, s[10:11]
	v_mov_b64_e32 v[34:35], v[6:7]
	v_mov_b64_e32 v[38:39], v[10:11]
	v_mov_b64_e32 v[42:43], v[14:15]
	v_mov_b64_e32 v[46:47], v[18:19]
	v_mov_b64_e32 v[32:33], v[4:5]
	v_mov_b64_e32 v[36:37], v[8:9]
	v_mov_b64_e32 v[40:41], v[12:13]
	v_mov_b64_e32 v[44:45], v[16:17]
	s_waitcnt vmcnt(2)
	v_pk_mul_f32 v[60:61], v[76:77], v[60:61]
	v_pk_mul_f32 v[62:63], v[102:103], v[62:63]
	s_waitcnt vmcnt(1)
	v_pk_add_f32 v[76:77], v[96:97], 1.0 op_sel_hi:[1,0]
	v_pk_add_f32 v[94:95], v[94:95], 1.0 op_sel_hi:[1,0]
	s_waitcnt vmcnt(0)
	v_pk_fma_f32 v[62:63], v[62:63], v[76:77], v[100:101]
	v_pk_fma_f32 v[60:61], v[60:61], v[94:95], v[98:99]
	v_bfe_u32 v93, v62, 16, 1
	v_bfe_u32 v76, v60, 16, 1
	v_bfe_u32 v77, v61, 16, 1
	v_bfe_u32 v94, v63, 16, 1
	v_add3_u32 v60, v60, v76, s61
	v_add3_u32 v62, v62, v93, s61
	v_add3_u32 v61, v61, v77, s61
	v_add3_u32 v63, v63, v94, s61
	v_lshrrev_b32_e32 v60, 16, v60
	v_lshrrev_b32_e32 v62, 16, v62
	v_and_or_b32 v60, v61, s86, v60
	v_and_or_b32 v61, v63, s86, v62
	global_store_dwordx2 v[74:75], v[60:61], off offset:3584
	v_mov_b64_e32 v[62:63], v[30:31]
	v_lshl_add_u64 v[74:75], v[74:75], 0, s[4:5]
	v_mov_b64_e32 v[60:61], v[28:29]
	s_cbranch_vccz .LBB0_153

; #define GAS __attribute__((address_space(1)))
; __device__ __forceinline__ unsigned pk2(float lo, float hi) { return f2bf(lo) | (f2bf(hi) << 16); }
; __device__ __forceinline__ float lane_read(float v, int src_lane) { return __builtin_bit_cast(float, __builtin_amdgcn_ds_bpermute(src_lane << 2, __builtin_bit_cast(int, v))); }
; __device__ __forceinline__ float wave_sum(float v, int lane) {
; #pragma unroll
;     for (int o = 1; o < 64; o <<= 1) v += lane_read(v, lane ^ o);
;     return v;
; }
;     ...
;     for (int row = row_lo + gw; row < nrows; row += NGW) {
;         const int s = row < SEQ ? 0 : row < ML ? 1 : 2;
;         const GAS float* shp = MOD + (size_t)s * (NMOD * DM) + (which ? 3 : 0) * DM; const GAS float* scp = shp + DM;
;         f32x4 v[8]; float ss = 0.f;
; #pragma unroll
;         for (int j = 0; j < 8; ++j) v[j] = nv[j];
;         { const int nrow = row + NGW; if (nrow < nrows) { const GAS float* xn = nrow < ML ? xl + (size_t)nrow * DM : xc + (size_t)(nrow - ML) * DM;
; #pragma unroll
;             for (int j = 0; j < 8; ++j) nv[j] = *(const GAS f32x4*)(xn + 4 * (F.lane + 64 * j)); } }
;         __builtin_amdgcn_sched_barrier(0);
;         if (row >= ML && nslab > 0) {
;             const GAS float* sl = WSP(float, WS_SLAB) + (size_t)(row - ML) * DM; GAS float* xw = WSP(float, WS_XC) + (size_t)(row - ML) * DM;
;             for (int ks = 0; ks < nslab; ++ks)
; #pragma unroll
;                 for (int j = 0; j < 8; ++j) v[j] += *(const GAS f32x4*)(sl + (size_t)ks * MC * DM + 4 * (F.lane + 64 * j));
; #pragma unroll
;             for (int j = 0; j < 8; ++j) *(GAS f32x4*)(xw + 4 * (F.lane + 64 * j)) = v[j];
;         }
; #pragma unroll
;         for (int j = 0; j < 8; ++j) ss += (v[j].x * v[j].x + v[j].y * v[j].y) + (v[j].z * v[j].z + v[j].w * v[j].w);
;         const float rstd = 1.0f / sqrtf(wave_sum(ss, F.lane) * (1.0f / DM) + EPS);
;         GAS bf16* hr = H + (size_t)row * DM;
; #pragma unroll
;         for (int j = 0; j < 8; ++j) { const int k = 4 * (F.lane + 64 * j);
;             const f32x4 g = *(const GAS f32x4*)(gain + k), sc = *(const GAS f32x4*)(scp + k), sh = *(const GAS f32x4*)(shp + k);
;             const f32x4 y = (v[j] * rstd * g) * (1.0f + sc) + sh;
;             v2u o; o.x = pk2(y.x, y.y); o.y = pk2(y.z, y.w); *(GAS v2u*)(hr + k) = o; }
.LBB0_157:
	s_cmp_lt_i32 s6, 0x8000
	s_movk_i32 s4, 0x3000
	s_cselect_b32 s4, s4, 0x6000
	s_cmpk_gt_i32 s6, 0x3fff
	s_cselect_b32 s4, s4, 0
	s_lshl_b32 s4, s4, 2
	s_add_u32 s12, s2, s4
	s_addc_u32 s13, s3, 0
	s_add_u32 s14, s12, 0x2000
	s_addc_u32 s15, s13, 0
	s_add_i32 s6, s6, s16
	v_mov_b32_e32 v98, v57
	v_mov_b32_e32 v99, v61
	v_mov_b32_e32 v96, v56
	v_mov_b32_e32 v97, v60
	v_pk_mul_f32 v[98:99], v[98:99], v[98:99]
	v_mov_b32_e32 v100, v59
	v_mov_b32_e32 v101, v63
	v_pk_fma_f32 v[96:97], v[96:97], v[96:97], v[98:99]
	v_mov_b32_e32 v98, v58
	v_mov_b32_e32 v99, v62
	v_pk_mul_f32 v[100:101], v[100:101], v[100:101]
	v_mul_f32_e32 v86, v48, v48
	v_pk_fma_f32 v[98:99], v[98:99], v[98:99], v[100:101]
	v_pk_mul_f32 v[100:101], v[52:53], v[52:53]
	v_pk_add_f32 v[96:97], v[96:97], v[98:99]
	v_pk_mul_f32 v[98:99], v[54:55], v[54:55]
	v_pk_add_f32 v[96:97], v[96:97], v[96:97] op_sel_hi:[0,1]
	v_pk_mov_b32 v[102:103], v[100:101], v[98:99] op_sel:[1,0]
	v_mov_b32_e32 v101, v99
	v_pk_add_f32 v[98:99], v[102:103], v[100:101]
	v_pk_fma_f32 v[100:101], v[48:49], v[48:49], v[86:87] op_sel_hi:[1,1,0]
	v_mul_f32_e32 v86, v50, v50
	v_pk_add_f32 v[98:99], v[98:99], v[98:99] op_sel_hi:[0,1]
	v_pk_fma_f32 v[102:103], v[50:51], v[50:51], v[86:87] op_sel_hi:[1,1,0]
	v_mul_f32_e32 v100, v44, v44
	v_mul_f32_e32 v102, v45, v45
	v_mul_f32_e32 v98, v46, v46
	v_mul_f32_e32 v96, v47, v47
	v_pk_add_f32 v[100:101], v[100:101], v[102:103]
	v_pk_add_f32 v[96:97], v[98:99], v[96:97]
	v_pk_mul_f32 v[98:99], v[42:43], v[42:43]
	v_pk_add_f32 v[96:97], v[100:101], v[96:97]
	v_pk_mul_f32 v[100:101], v[40:41], v[40:41]
	v_mul_f32_e32 v86, v4, v4
	v_pk_mov_b32 v[102:103], v[100:101], v[98:99] op_sel:[1,0]
	v_mov_b32_e32 v101, v99
	v_pk_add_f32 v[98:99], v[102:103], v[100:101]
	v_pk_fma_f32 v[100:101], v[4:5], v[4:5], v[86:87] op_sel_hi:[1,1,0]
	v_mul_f32_e32 v86, v6, v6
	v_pk_add_f32 v[96:97], v[96:97], v[96:97] op_sel_hi:[0,1]
	v_pk_add_f32 v[98:99], v[98:99], v[98:99] op_sel_hi:[0,1]
	v_pk_fma_f32 v[102:103], v[6:7], v[6:7], v[86:87] op_sel_hi:[1,1,0]
	v_mul_f32_e32 v100, v0, v0
	v_mul_f32_e32 v102, v1, v1
	v_mul_f32_e32 v98, v2, v2
	v_mul_f32_e32 v96, v3, v3
	v_pk_add_f32 v[100:101], v[100:101], v[102:103]
	v_pk_add_f32 v[102:103], v[98:99], v[96:97]
	global_load_dwordx4 v[96:99], v[74:75], off
	v_pk_add_f32 v[104:105], v[100:101], v[102:103]
	global_load_dwordx4 v[100:103], v95, s[14:15]
	v_add_f32_e32 v86, v104, v105
	global_load_dwordx4 v[104:107], v95, s[12:13]
	s_nop 1
	v_readlane_b32 s16, v255, 22
	v_readlane_b32 s17, v255, 23
	s_add_u32 s0, s0, s16
	s_addc_u32 s7, s7, s17
	v_add_f32_dpp v86, v86, v86 row_shr:1 row_mask:0xf bank_mask:0xf bound_ctrl:0
	s_nop 1
	s_cmp_gt_i32 s6, 0x81ff
	v_add_f32_dpp v86, v86, v86 row_shr:2 row_mask:0xf bank_mask:0xf bound_ctrl:0
	s_nop 1
	v_add_f32_dpp v86, v86, v86 row_shr:4 row_mask:0xf bank_mask:0xf bound_ctrl:0
	s_nop 1
	v_add_f32_dpp v86, v86, v86 row_shr:8 row_mask:0xf bank_mask:0xf bound_ctrl:0
	s_nop 1
	v_add_f32_dpp v86, v86, v86 row_bcast:15 row_mask:0xa bank_mask:0xf
	s_nop 1
	v_add_f32_dpp v86, v86, v86 row_bcast:31 row_mask:0xc bank_mask:0xf
	s_nop 0
	v_readlane_b32 s4, v86, 63
	s_nop 1
	v_mov_b32_e32 v86, s4
	v_fmamk_f32 v86, v86, 0x3a000000, v212
	v_mul_f32_e32 v108, 0x4f800000, v86
	v_cmp_gt_f32_e32 vcc, s60, v86
	s_nop 1
	v_cndmask_b32_e32 v86, v86, v108, vcc
	v_sqrt_f32_e32 v108, v86
	s_nop 0
	v_add_u32_e32 v109, -1, v108
	v_fma_f32 v110, -v109, v108, v86
	v_cmp_ge_f32_e64 s[4:5], 0, v110
	v_add_u32_e32 v110, 1, v108
	s_nop 0
	v_cndmask_b32_e64 v109, v108, v109, s[4:5]
	v_fma_f32 v108, -v110, v108, v86
	v_cmp_lt_f32_e64 s[4:5], 0, v108
	s_nop 1
	v_cndmask_b32_e64 v108, v109, v110, s[4:5]
	v_mul_f32_e32 v109, 0x37800000, v108
	v_cndmask_b32_e32 v108, v108, v109, vcc
	v_cmp_class_f32_e32 vcc, v86, v213
	s_nop 1
	v_cndmask_b32_e32 v86, v108, v86, vcc
	v_div_scale_f32 v108, s[4:5], v86, v86, 1.0
	v_rcp_f32_e32 v109, v108
	v_readlane_b32 s4, v255, 24
	v_readlane_b32 s5, v255, 25
	v_fma_f32 v110, -v108, v109, 1.0
	v_fmac_f32_e32 v109, v110, v109
	v_div_scale_f32 v110, vcc, 1.0, v86, 1.0
	v_mul_f32_e32 v111, v110, v109
	v_fma_f32 v112, -v108, v111, v110
	v_fmac_f32_e32 v111, v112, v109
	v_fma_f32 v108, -v108, v111, v110
	v_div_fmas_f32 v108, v108, v109, v111
	v_div_fixup_f32 v86, v108, v86, 1.0
	v_pk_mul_f32 v[62:63], v[62:63], v[86:87] op_sel_hi:[1,0]
	v_pk_mul_f32 v[60:61], v[60:61], v[86:87] op_sel_hi:[1,0]
	s_waitcnt vmcnt(2)
	v_pk_mul_f32 v[62:63], v[98:99], v[62:63]
	v_pk_mul_f32 v[60:61], v[96:97], v[60:61]
	s_waitcnt vmcnt(1)
	v_pk_add_f32 v[98:99], v[100:101], 1.0 op_sel_hi:[1,0]
	v_pk_add_f32 v[96:97], v[102:103], 1.0 op_sel_hi:[1,0]
	s_waitcnt vmcnt(0)
	v_pk_fma_f32 v[60:61], v[98:99], v[60:61], v[104:105]
	v_pk_fma_f32 v[62:63], v[96:97], v[62:63], v[106:107]
	v_bfe_u32 v96, v60, 16, 1
	v_add3_u32 v60, v60, v96, s61
	v_bfe_u32 v96, v61, 16, 1
	v_lshrrev_b32_e32 v60, 16, v60
	v_add3_u32 v61, v61, v96, s61
	v_and_or_b32 v60, v61, s86, v60
	v_bfe_u32 v61, v62, 16, 1
	v_add3_u32 v61, v62, v61, s61
	v_bfe_u32 v62, v63, 16, 1
	v_lshrrev_b32_e32 v61, 16, v61
	v_add3_u32 v62, v63, v62, s61
	v_and_or_b32 v61, v62, s86, v61
	global_store_dwordx2 v[84:85], v[60:61], off
	global_load_dwordx4 v[60:63], v[74:75], off offset:1024
	s_nop 0
	global_load_dwordx4 v[96:99], v88, s[14:15]
	global_load_dwordx4 v[100:103], v95, s[12:13] offset:1024
	v_pk_mul_f32 v[58:59], v[58:59], v[86:87] op_sel_hi:[1,0]
	v_pk_mul_f32 v[56:57], v[56:57], v[86:87] op_sel_hi:[1,0]
	v_pk_mul_f32 v[54:55], v[54:55], v[86:87] op_sel_hi:[1,0]
	v_pk_mul_f32 v[52:53], v[52:53], v[86:87] op_sel_hi:[1,0]
	v_pk_mul_f32 v[50:51], v[50:51], v[86:87] op_sel_hi:[1,0]
	v_pk_mul_f32 v[48:49], v[48:49], v[86:87] op_sel_hi:[1,0]
	v_pk_mul_f32 v[46:47], v[46:47], v[86:87] op_sel_hi:[1,0]
	v_pk_mul_f32 v[44:45], v[44:45], v[86:87] op_sel_hi:[1,0]
	v_pk_mul_f32 v[42:43], v[42:43], v[86:87] op_sel_hi:[1,0]
	v_pk_mul_f32 v[40:41], v[40:41], v[86:87] op_sel_hi:[1,0]
	v_pk_mul_f32 v[6:7], v[6:7], v[86:87] op_sel_hi:[1,0]
	v_pk_mul_f32 v[4:5], v[4:5], v[86:87] op_sel_hi:[1,0]
	s_waitcnt vmcnt(2)
; #define GAS __attribute__((address_space(1)))
; __device__ __forceinline__ unsigned f2bf(float f) { unsigned u = __builtin_bit_cast(unsigned, f); return (u + 0x7fffu + ((u >> 16) & 1u)) >> 16; }
; __device__ __forceinline__ unsigned pk2(float lo, float hi) { return f2bf(lo) | (f2bf(hi) << 16); }
;     ...
;         GAS bf16* hr = H + (size_t)row * DM;
; #pragma unroll
;         for (int j = 0; j < 8; ++j) { const int k = 4 * (F.lane + 64 * j);
;             const f32x4 g = *(const GAS f32x4*)(gain + k), sc = *(const GAS f32x4*)(scp + k), sh = *(const GAS f32x4*)(shp + k);
;             const f32x4 y = (v[j] * rstd * g) * (1.0f + sc) + sh;
;             v2u o; o.x = pk2(y.x, y.y); o.y = pk2(y.z, y.w); *(GAS v2u*)(hr + k) = o; }
	v_pk_mul_f32 v[56:57], v[60:61], v[56:57]
	v_pk_mul_f32 v[58:59], v[62:63], v[58:59]
	s_waitcnt vmcnt(1)
	v_pk_add_f32 v[60:61], v[98:99], 1.0 op_sel_hi:[1,0]
	v_pk_add_f32 v[62:63], v[96:97], 1.0 op_sel_hi:[1,0]
	s_waitcnt vmcnt(0)
	v_pk_fma_f32 v[58:59], v[60:61], v[58:59], v[102:103]
	v_pk_fma_f32 v[56:57], v[62:63], v[56:57], v[100:101]
	v_bfe_u32 v62, v58, 16, 1
	v_bfe_u32 v60, v56, 16, 1
	v_bfe_u32 v61, v57, 16, 1
	v_bfe_u32 v63, v59, 16, 1
	v_add3_u32 v56, v56, v60, s61
	v_add3_u32 v58, v58, v62, s61
	v_add3_u32 v57, v57, v61, s61
	v_add3_u32 v59, v59, v63, s61
	v_lshrrev_b32_e32 v56, 16, v56
	v_lshrrev_b32_e32 v58, 16, v58
	v_and_or_b32 v56, v57, s86, v56
	v_and_or_b32 v57, v59, s86, v58
	global_store_dwordx2 v[84:85], v[56:57], off offset:512
	global_load_dwordx4 v[56:59], v[74:75], off offset:2048
	s_nop 0
	global_load_dwordx4 v[60:63], v89, s[14:15]
	global_load_dwordx4 v[96:99], v95, s[12:13] offset:2048
	v_pk_mul_f32 v[100:101], v[2:3], v[86:87] op_sel_hi:[1,0]
	v_pk_mul_f32 v[102:103], v[0:1], v[86:87] op_sel_hi:[1,0]
	v_mov_b64_e32 v[0:1], v[8:9]
	v_mov_b64_e32 v[2:3], v[10:11]
	s_waitcnt vmcnt(2)
	v_pk_mul_f32 v[52:53], v[52:53], v[56:57]
	v_pk_mul_f32 v[54:55], v[54:55], v[58:59]
	s_waitcnt vmcnt(1)
	v_pk_add_f32 v[56:57], v[62:63], 1.0 op_sel_hi:[1,0]
	v_pk_add_f32 v[58:59], v[60:61], 1.0 op_sel_hi:[1,0]
	s_waitcnt vmcnt(0)
	v_pk_fma_f32 v[54:55], v[54:55], v[56:57], v[98:99]
	v_pk_fma_f32 v[52:53], v[52:53], v[58:59], v[96:97]
	v_bfe_u32 v58, v54, 16, 1
	v_bfe_u32 v56, v52, 16, 1
	v_bfe_u32 v57, v53, 16, 1
	v_bfe_u32 v59, v55, 16, 1
	v_add3_u32 v52, v52, v56, s61
	v_add3_u32 v54, v54, v58, s61
	v_add3_u32 v53, v53, v57, s61
	v_add3_u32 v55, v55, v59, s61
	v_lshrrev_b32_e32 v52, 16, v52
	v_lshrrev_b32_e32 v54, 16, v54
	v_and_or_b32 v52, v53, s86, v52
	v_and_or_b32 v53, v55, s86, v54
	global_store_dwordx2 v[84:85], v[52:53], off offset:1024
	global_load_dwordx4 v[52:55], v[74:75], off offset:3072
	s_nop 0
	global_load_dwordx4 v[56:59], v90, s[14:15]
	global_load_dwordx4 v[60:63], v95, s[12:13] offset:3072
	s_waitcnt vmcnt(2)
	v_pk_mul_f32 v[48:49], v[48:49], v[52:53]
	v_pk_mul_f32 v[50:51], v[50:51], v[54:55]
	s_waitcnt vmcnt(1)
	v_pk_add_f32 v[52:53], v[58:59], 1.0 op_sel_hi:[1,0]
	v_pk_add_f32 v[54:55], v[56:57], 1.0 op_sel_hi:[1,0]
	s_waitcnt vmcnt(0)
	v_pk_fma_f32 v[50:51], v[50:51], v[52:53], v[62:63]
	v_pk_fma_f32 v[48:49], v[48:49], v[54:55], v[60:61]
	v_bfe_u32 v54, v50, 16, 1
	v_bfe_u32 v52, v48, 16, 1
	v_bfe_u32 v53, v49, 16, 1
	v_bfe_u32 v55, v51, 16, 1
	v_add3_u32 v48, v48, v52, s61
	v_add3_u32 v50, v50, v54, s61
	v_add3_u32 v49, v49, v53, s61
	v_add3_u32 v51, v51, v55, s61
	v_lshrrev_b32_e32 v48, 16, v48
	v_lshrrev_b32_e32 v50, 16, v50
	v_and_or_b32 v48, v49, s86, v48
	v_and_or_b32 v49, v51, s86, v50
	global_store_dwordx2 v[84:85], v[48:49], off offset:1536
	global_load_dwordx4 v[48:51], v[76:77], off
	s_nop 0
	global_load_dwordx4 v[52:55], v94, s[14:15]
	global_load_dwordx4 v[56:59], v94, s[12:13]
	s_waitcnt vmcnt(2)
	v_pk_mul_f32 v[44:45], v[44:45], v[48:49]
	v_pk_mul_f32 v[46:47], v[46:47], v[50:51]
	s_waitcnt vmcnt(1)
	v_pk_add_f32 v[48:49], v[54:55], 1.0 op_sel_hi:[1,0]
	v_pk_add_f32 v[50:51], v[52:53], 1.0 op_sel_hi:[1,0]
	s_waitcnt vmcnt(0)
	v_pk_fma_f32 v[46:47], v[46:47], v[48:49], v[58:59]
	v_pk_fma_f32 v[44:45], v[44:45], v[50:51], v[56:57]
	v_bfe_u32 v50, v46, 16, 1
	v_bfe_u32 v48, v44, 16, 1
	v_bfe_u32 v49, v45, 16, 1
	v_bfe_u32 v51, v47, 16, 1
	v_add3_u32 v44, v44, v48, s61
	v_add3_u32 v46, v46, v50, s61
	v_add3_u32 v45, v45, v49, s61
	v_add3_u32 v47, v47, v51, s61
	v_lshrrev_b32_e32 v44, 16, v44
	v_lshrrev_b32_e32 v46, 16, v46
	v_and_or_b32 v44, v45, s86, v44
	v_and_or_b32 v45, v47, s86, v46
	global_store_dwordx2 v[84:85], v[44:45], off offset:2048
	global_load_dwordx4 v[44:47], v[78:79], off
	s_nop 0
	global_load_dwordx4 v[48:51], v93, s[14:15]
	global_load_dwordx4 v[52:55], v93, s[12:13]
	v_mov_b64_e32 v[58:59], v[34:35]
	v_mov_b64_e32 v[56:57], v[32:33]
	s_waitcnt vmcnt(2)
	v_pk_mul_f32 v[40:41], v[40:41], v[44:45]
	v_pk_mul_f32 v[42:43], v[42:43], v[46:47]
	s_waitcnt vmcnt(1)
	v_pk_add_f32 v[44:45], v[50:51], 1.0 op_sel_hi:[1,0]
	v_pk_add_f32 v[46:47], v[48:49], 1.0 op_sel_hi:[1,0]
	s_waitcnt vmcnt(0)
	v_pk_fma_f32 v[42:43], v[42:43], v[44:45], v[54:55]
	v_pk_fma_f32 v[40:41], v[40:41], v[46:47], v[52:53]
	v_bfe_u32 v46, v42, 16, 1
	v_bfe_u32 v44, v40, 16, 1
	v_bfe_u32 v45, v41, 16, 1
	v_bfe_u32 v47, v43, 16, 1
	v_add3_u32 v40, v40, v44, s61
	v_add3_u32 v42, v42, v46, s61
	v_add3_u32 v41, v41, v45, s61
	v_add3_u32 v43, v43, v47, s61
	v_lshrrev_b32_e32 v40, 16, v40
	v_lshrrev_b32_e32 v42, 16, v42
	v_and_or_b32 v40, v41, s86, v40
	v_and_or_b32 v41, v43, s86, v42
	global_store_dwordx2 v[84:85], v[40:41], off offset:2560
	global_load_dwordx4 v[40:43], v[80:81], off
	s_nop 0
	global_load_dwordx4 v[44:47], v92, s[14:15]
	global_load_dwordx4 v[48:51], v92, s[12:13]
	v_mov_b64_e32 v[54:55], v[30:31]
	v_mov_b64_e32 v[52:53], v[28:29]
	s_waitcnt vmcnt(2)
	v_pk_mul_f32 v[4:5], v[4:5], v[40:41]
	v_pk_mul_f32 v[6:7], v[6:7], v[42:43]
	s_waitcnt vmcnt(1)
	v_pk_add_f32 v[40:41], v[46:47], 1.0 op_sel_hi:[1,0]
	v_pk_add_f32 v[42:43], v[44:45], 1.0 op_sel_hi:[1,0]
	s_waitcnt vmcnt(0)
	v_pk_fma_f32 v[6:7], v[6:7], v[40:41], v[50:51]
	v_pk_fma_f32 v[4:5], v[4:5], v[42:43], v[48:49]
	v_bfe_u32 v42, v6, 16, 1
	v_bfe_u32 v40, v4, 16, 1
	v_bfe_u32 v41, v5, 16, 1
	v_bfe_u32 v43, v7, 16, 1
	v_add3_u32 v4, v4, v40, s61
	v_add3_u32 v6, v6, v42, s61
	v_add3_u32 v5, v5, v41, s61
	v_add3_u32 v7, v7, v43, s61
	v_lshrrev_b32_e32 v4, 16, v4
	v_lshrrev_b32_e32 v6, 16, v6
	v_and_or_b32 v4, v5, s86, v4
	v_and_or_b32 v5, v7, s86, v6
	global_store_dwordx2 v[84:85], v[4:5], off offset:3072
	global_load_dwordx4 v[60:63], v[82:83], off
	global_load_dwordx4 v[92:95], v91, s[14:15]
	global_load_dwordx4 v[96:99], v91, s[12:13]
	v_mov_b64_e32 v[4:5], v[12:13]
	v_mov_b64_e32 v[42:43], v[18:19]
	v_mov_b64_e32 v[46:47], v[22:23]
	v_mov_b64_e32 v[50:51], v[26:27]
	v_mov_b64_e32 v[6:7], v[14:15]
	v_mov_b64_e32 v[40:41], v[16:17]
	v_mov_b64_e32 v[44:45], v[20:21]
	v_mov_b64_e32 v[48:49], v[24:25]
	s_waitcnt vmcnt(2)
	v_pk_mul_f32 v[60:61], v[102:103], v[60:61]
	v_pk_mul_f32 v[62:63], v[100:101], v[62:63]
	s_waitcnt vmcnt(1)
	v_pk_add_f32 v[94:95], v[94:95], 1.0 op_sel_hi:[1,0]
	v_pk_add_f32 v[92:93], v[92:93], 1.0 op_sel_hi:[1,0]
	s_waitcnt vmcnt(0)
	v_pk_fma_f32 v[62:63], v[62:63], v[94:95], v[98:99]
	v_pk_fma_f32 v[60:61], v[60:61], v[92:93], v[96:97]
	v_bfe_u32 v92, v62, 16, 1
	v_bfe_u32 v86, v60, 16, 1
	v_bfe_u32 v91, v61, 16, 1
	v_bfe_u32 v93, v63, 16, 1
	v_add3_u32 v60, v60, v86, s61
	v_add3_u32 v62, v62, v92, s61
	v_add3_u32 v61, v61, v91, s61
	v_add3_u32 v63, v63, v93, s61
	v_lshrrev_b32_e32 v60, 16, v60
	v_lshrrev_b32_e32 v62, 16, v62
	v_and_or_b32 v60, v61, s86, v60
	v_and_or_b32 v61, v63, s86, v62
	global_store_dwordx2 v[84:85], v[60:61], off offset:3584
	v_mov_b64_e32 v[62:63], v[38:39]
	v_lshl_add_u64 v[84:85], v[84:85], 0, s[4:5]
	v_mov_b64_e32 v[60:61], v[36:37]
	s_cbranch_scc1 .LBB0_160

; #define GAS __attribute__((address_space(1)))
; __device__ __forceinline__ unsigned pk2(float lo, float hi) { return f2bf(lo) | (f2bf(hi) << 16); }
; __device__ __forceinline__ float lane_read(float v, int src_lane) { return __builtin_bit_cast(float, __builtin_amdgcn_ds_bpermute(src_lane << 2, __builtin_bit_cast(int, v))); }
; __device__ __forceinline__ float wave_sum(float v, int lane) {
; #pragma unroll
;     for (int o = 1; o < 64; o <<= 1) v += lane_read(v, lane ^ o);
;     return v;
; }
;     ...
;     for (int row = row_lo + gw; row < nrows; row += NGW) {
;         const int s = row < SEQ ? 0 : row < ML ? 1 : 2;
;         const GAS float* shp = MOD + (size_t)s * (NMOD * DM) + (which ? 3 : 0) * DM; const GAS float* scp = shp + DM;
;         f32x4 v[8]; float ss = 0.f;
; #pragma unroll
;         for (int j = 0; j < 8; ++j) v[j] = nv[j];
;         { const int nrow = row + NGW; if (nrow < nrows) { const GAS float* xn = nrow < ML ? xl + (size_t)nrow * DM : xc + (size_t)(nrow - ML) * DM;
; #pragma unroll
;             for (int j = 0; j < 8; ++j) nv[j] = *(const GAS f32x4*)(xn + 4 * (F.lane + 64 * j)); } }
;         __builtin_amdgcn_sched_barrier(0);
;         if (row >= ML && nslab > 0) {
;             const GAS float* sl = WSP(float, WS_SLAB) + (size_t)(row - ML) * DM; GAS float* xw = WSP(float, WS_XC) + (size_t)(row - ML) * DM;
;             for (int ks = 0; ks < nslab; ++ks)
; #pragma unroll
;                 for (int j = 0; j < 8; ++j) v[j] += *(const GAS f32x4*)(sl + (size_t)ks * MC * DM + 4 * (F.lane + 64 * j));
; #pragma unroll
;             for (int j = 0; j < 8; ++j) *(GAS f32x4*)(xw + 4 * (F.lane + 64 * j)) = v[j];
;         }
; #pragma unroll
;         for (int j = 0; j < 8; ++j) ss += (v[j].x * v[j].x + v[j].y * v[j].y) + (v[j].z * v[j].z + v[j].w * v[j].w);
;         const float rstd = 1.0f / sqrtf(wave_sum(ss, F.lane) * (1.0f / DM) + EPS);
;         GAS bf16* hr = H + (size_t)row * DM;
; #pragma unroll
;         for (int j = 0; j < 8; ++j) { const int k = 4 * (F.lane + 64 * j);
;             const f32x4 g = *(const GAS f32x4*)(gain + k), sc = *(const GAS f32x4*)(scp + k), sh = *(const GAS f32x4*)(shp + k);
;             const f32x4 y = (v[j] * rstd * g) * (1.0f + sc) + sh;
;             v2u o; o.x = pk2(y.x, y.y); o.y = pk2(y.z, y.w); *(GAS v2u*)(hr + k) = o; }
.LBB0_1384:
	v_pk_mul_f32 v[102:103], v[60:61], v[60:61]
	v_pk_mul_f32 v[104:105], v[56:57], v[56:57]
	v_pk_mul_f32 v[98:99], v[62:63], v[62:63]
	v_pk_mul_f32 v[100:101], v[58:59], v[58:59]
	v_mov_b32_e32 v106, v102
	v_mov_b32_e32 v107, v104
	v_mov_b32_e32 v104, v103
	v_pk_mul_f32 v[94:95], v[54:55], v[54:55]
	v_pk_mul_f32 v[96:97], v[52:53], v[52:53]
	v_pk_add_f32 v[102:103], v[106:107], v[104:105]
	v_mov_b32_e32 v104, v98
	v_mov_b32_e32 v105, v100
	v_mov_b32_e32 v100, v99
	v_pk_add_f32 v[98:99], v[104:105], v[100:101]
	v_pk_mov_b32 v[100:101], v[96:97], v[94:95] op_sel:[1,0]
	v_mov_b32_e32 v97, v95
	v_pk_add_f32 v[94:95], v[100:101], v[96:97]
	v_pk_add_f32 v[98:99], v[102:103], v[98:99]
	v_pk_add_f32 v[94:95], v[94:95], v[94:95] op_sel_hi:[0,1]
	v_mul_f32_e32 v94, v44, v44
	v_pk_fma_f32 v[96:97], v[44:45], v[44:45], v[94:95] op_sel_hi:[1,1,0]
	v_mul_f32_e32 v94, v46, v46
	v_pk_add_f32 v[98:99], v[98:99], v[98:99] op_sel_hi:[0,1]
	v_pk_fma_f32 v[100:101], v[46:47], v[46:47], v[94:95] op_sel_hi:[1,1,0]
	v_mul_f32_e32 v96, v40, v40
	v_mul_f32_e32 v100, v41, v41
	v_mul_f32_e32 v94, v42, v42
	v_mul_f32_e32 v98, v43, v43
	v_pk_mul_f32 v[76:77], v[38:39], v[38:39]
	v_pk_mul_f32 v[92:93], v[36:37], v[36:37]
	v_pk_add_f32 v[96:97], v[96:97], v[100:101]
	v_pk_add_f32 v[94:95], v[94:95], v[98:99]
	s_cmp_lt_i32 s10, 0x8000
	s_movk_i32 s6, 0x3000
	v_pk_add_f32 v[94:95], v[96:97], v[94:95]
	v_pk_mov_b32 v[96:97], v[92:93], v[76:77] op_sel:[1,0]
	v_mov_b32_e32 v93, v77
	s_cselect_b32 s6, s6, 0x6000
	s_cmpk_gt_i32 s10, 0x3fff
	v_pk_add_f32 v[76:77], v[96:97], v[92:93]
	s_cselect_b32 s6, s6, 0
	v_pk_add_f32 v[76:77], v[76:77], v[76:77] op_sel_hi:[0,1]
	s_lshl_b32 s6, s6, 2
	v_mul_f32_e32 v76, v32, v32
	s_add_u32 s8, s3, s6
	v_pk_fma_f32 v[92:93], v[32:33], v[32:33], v[76:77] op_sel_hi:[1,1,0]
	v_mul_f32_e32 v76, v34, v34
	s_addc_u32 s9, s12, 0
	v_pk_add_f32 v[94:95], v[94:95], v[94:95] op_sel_hi:[0,1]
	v_pk_fma_f32 v[96:97], v[34:35], v[34:35], v[76:77] op_sel_hi:[1,1,0]
	s_add_u32 s10, s8, 0x2000
	v_mul_f32_e32 v92, v48, v48
	v_mul_f32_e32 v96, v49, v49
	v_mul_f32_e32 v76, v50, v50
	v_mul_f32_e32 v94, v51, v51
	s_addc_u32 s11, s9, 0
	v_pk_add_f32 v[96:97], v[92:93], v[96:97]
	v_pk_add_f32 v[76:77], v[76:77], v[94:95]
	global_load_dwordx4 v[92:95], v[64:65], off
	v_pk_add_f32 v[76:77], v[96:97], v[76:77]
	global_load_dwordx4 v[96:99], v84, s[10:11]
	global_load_dwordx4 v[100:103], v84, s[8:9]
	v_add_f32_e32 v76, v76, v77
	s_nop 1
	v_readlane_b32 s20, v255, 22
	v_readlane_b32 s21, v255, 23
	s_add_u32 s17, s17, s20
	s_addc_u32 s18, s18, s21
	v_add_f32_dpp v76, v76, v76 row_shr:1 row_mask:0xf bank_mask:0xf bound_ctrl:0
	s_nop 1
	s_mov_b32 s50, s19
	v_add_f32_dpp v76, v76, v76 row_shr:2 row_mask:0xf bank_mask:0xf bound_ctrl:0
	s_nop 1
	v_add_f32_dpp v76, v76, v76 row_shr:4 row_mask:0xf bank_mask:0xf bound_ctrl:0
	s_nop 1
	v_add_f32_dpp v76, v76, v76 row_shr:8 row_mask:0xf bank_mask:0xf bound_ctrl:0
	s_nop 1
	v_add_f32_dpp v76, v76, v76 row_bcast:15 row_mask:0xa bank_mask:0xf
	s_nop 1
	v_add_f32_dpp v76, v76, v76 row_bcast:31 row_mask:0xc bank_mask:0xf
	s_nop 0
	v_readlane_b32 s6, v76, 63
	s_nop 1
	v_mov_b32_e32 v76, s6
	v_fmamk_f32 v76, v76, 0x3a000000, v212
	v_mul_f32_e32 v77, 0x4f800000, v76
	v_cmp_gt_f32_e32 vcc, s60, v76
	s_nop 1
	v_cndmask_b32_e32 v76, v76, v77, vcc
	v_sqrt_f32_e32 v77, v76
	s_nop 0
	v_add_u32_e32 v104, -1, v77
	v_fma_f32 v105, -v104, v77, v76
	v_cmp_ge_f32_e64 s[6:7], 0, v105
	v_add_u32_e32 v105, 1, v77
	s_nop 0
	v_cndmask_b32_e64 v104, v77, v104, s[6:7]
	v_fma_f32 v77, -v105, v77, v76
	v_cmp_lt_f32_e64 s[6:7], 0, v77
	s_nop 1
	v_cndmask_b32_e64 v77, v104, v105, s[6:7]
	v_mul_f32_e32 v104, 0x37800000, v77
	v_cndmask_b32_e32 v77, v77, v104, vcc
	v_cmp_class_f32_e32 vcc, v76, v213
	s_nop 1
	v_cndmask_b32_e32 v76, v77, v76, vcc
	v_div_scale_f32 v77, s[6:7], v76, v76, 1.0
	v_rcp_f32_e32 v104, v77
	s_nop 0
	v_fma_f32 v105, -v77, v104, 1.0
	v_fmac_f32_e32 v104, v105, v104
	v_div_scale_f32 v105, vcc, 1.0, v76, 1.0
	v_mul_f32_e32 v106, v105, v104
	v_fma_f32 v107, -v77, v106, v105
	v_fmac_f32_e32 v106, v107, v104
	v_fma_f32 v77, -v77, v106, v105
	v_div_fmas_f32 v77, v77, v104, v106
	v_div_fixup_f32 v76, v77, v76, 1.0
	v_pk_mul_f32 v[62:63], v[62:63], v[76:77] op_sel_hi:[1,0]
	v_pk_mul_f32 v[60:61], v[60:61], v[76:77] op_sel_hi:[1,0]
	s_waitcnt vmcnt(2)
	v_pk_mul_f32 v[62:63], v[94:95], v[62:63]
	v_pk_mul_f32 v[60:61], v[92:93], v[60:61]
	s_waitcnt vmcnt(1)
	v_pk_add_f32 v[94:95], v[96:97], 1.0 op_sel_hi:[1,0]
	v_pk_add_f32 v[92:93], v[98:99], 1.0 op_sel_hi:[1,0]
	s_waitcnt vmcnt(0)
	v_pk_fma_f32 v[60:61], v[94:95], v[60:61], v[100:101]
	v_pk_fma_f32 v[62:63], v[92:93], v[62:63], v[102:103]
	v_bfe_u32 v77, v60, 16, 1
	v_add3_u32 v60, v60, v77, s61
	v_bfe_u32 v77, v61, 16, 1
	v_lshrrev_b32_e32 v60, 16, v60
	v_add3_u32 v61, v61, v77, s61
	v_and_or_b32 v60, v61, s86, v60
	v_bfe_u32 v61, v62, 16, 1
	v_add3_u32 v61, v62, v61, s61
	v_bfe_u32 v62, v63, 16, 1
	v_lshrrev_b32_e32 v61, 16, v61
	v_add3_u32 v62, v63, v62, s61
	v_and_or_b32 v61, v62, s86, v61
	global_store_dwordx2 v[74:75], v[60:61], off
	global_load_dwordx4 v[60:63], v[64:65], off offset:1024
	s_nop 0
	global_load_dwordx4 v[92:95], v85, s[10:11]
	global_load_dwordx4 v[96:99], v84, s[8:9] offset:1024
	v_pk_mul_f32 v[58:59], v[58:59], v[76:77] op_sel_hi:[1,0]
	v_pk_mul_f32 v[56:57], v[56:57], v[76:77] op_sel_hi:[1,0]
	v_pk_mul_f32 v[54:55], v[54:55], v[76:77] op_sel_hi:[1,0]
	v_pk_mul_f32 v[52:53], v[52:53], v[76:77] op_sel_hi:[1,0]
	v_pk_mul_f32 v[46:47], v[46:47], v[76:77] op_sel_hi:[1,0]
	v_pk_mul_f32 v[44:45], v[44:45], v[76:77] op_sel_hi:[1,0]
	v_pk_mul_f32 v[42:43], v[42:43], v[76:77] op_sel_hi:[1,0]
	v_pk_mul_f32 v[40:41], v[40:41], v[76:77] op_sel_hi:[1,0]
	v_pk_mul_f32 v[38:39], v[38:39], v[76:77] op_sel_hi:[1,0]
	v_pk_mul_f32 v[36:37], v[36:37], v[76:77] op_sel_hi:[1,0]
	v_pk_mul_f32 v[34:35], v[34:35], v[76:77] op_sel_hi:[1,0]
	v_pk_mul_f32 v[32:33], v[32:33], v[76:77] op_sel_hi:[1,0]
	v_pk_mul_f32 v[100:101], v[50:51], v[76:77] op_sel_hi:[1,0]
	v_pk_mul_f32 v[76:77], v[48:49], v[76:77] op_sel_hi:[1,0]
	s_andn2_b64 vcc, exec, s[4:5]
	v_readlane_b32 s4, v255, 24
	v_mov_b64_e32 v[50:51], v[2:3]
	v_readlane_b32 s5, v255, 25
	v_mov_b64_e32 v[48:49], v[0:1]
	s_waitcnt vmcnt(2)
; #define GAS __attribute__((address_space(1)))
; __device__ __forceinline__ unsigned f2bf(float f) { unsigned u = __builtin_bit_cast(unsigned, f); return (u + 0x7fffu + ((u >> 16) & 1u)) >> 16; }
; __device__ __forceinline__ unsigned pk2(float lo, float hi) { return f2bf(lo) | (f2bf(hi) << 16); }
;     ...
;         GAS bf16* hr = H + (size_t)row * DM;
; #pragma unroll
;         for (int j = 0; j < 8; ++j) { const int k = 4 * (F.lane + 64 * j);
;             const f32x4 g = *(const GAS f32x4*)(gain + k), sc = *(const GAS f32x4*)(scp + k), sh = *(const GAS f32x4*)(shp + k);
;             const f32x4 y = (v[j] * rstd * g) * (1.0f + sc) + sh;
;             v2u o; o.x = pk2(y.x, y.y); o.y = pk2(y.z, y.w); *(GAS v2u*)(hr + k) = o; }
	v_pk_mul_f32 v[56:57], v[60:61], v[56:57]
	v_pk_mul_f32 v[58:59], v[62:63], v[58:59]
	s_waitcnt vmcnt(1)
	v_pk_add_f32 v[60:61], v[94:95], 1.0 op_sel_hi:[1,0]
	v_pk_add_f32 v[62:63], v[92:93], 1.0 op_sel_hi:[1,0]
	s_waitcnt vmcnt(0)
	v_pk_fma_f32 v[58:59], v[60:61], v[58:59], v[98:99]
	v_pk_fma_f32 v[56:57], v[62:63], v[56:57], v[96:97]
	v_bfe_u32 v62, v58, 16, 1
	v_bfe_u32 v60, v56, 16, 1
	v_bfe_u32 v61, v57, 16, 1
	v_bfe_u32 v63, v59, 16, 1
	v_add3_u32 v56, v56, v60, s61
	v_add3_u32 v58, v58, v62, s61
	v_add3_u32 v57, v57, v61, s61
	v_add3_u32 v59, v59, v63, s61
	v_lshrrev_b32_e32 v56, 16, v56
	v_lshrrev_b32_e32 v58, 16, v58
	v_and_or_b32 v56, v57, s86, v56
	v_and_or_b32 v57, v59, s86, v58
	global_store_dwordx2 v[74:75], v[56:57], off offset:512
	global_load_dwordx4 v[56:59], v[64:65], off offset:2048
	s_nop 0
	global_load_dwordx4 v[60:63], v86, s[10:11]
	global_load_dwordx4 v[92:95], v84, s[8:9] offset:2048
	s_waitcnt vmcnt(2)
	v_pk_mul_f32 v[52:53], v[56:57], v[52:53]
	v_pk_mul_f32 v[54:55], v[58:59], v[54:55]
	s_waitcnt vmcnt(1)
	v_pk_add_f32 v[56:57], v[62:63], 1.0 op_sel_hi:[1,0]
	v_pk_add_f32 v[58:59], v[60:61], 1.0 op_sel_hi:[1,0]
	s_waitcnt vmcnt(0)
	v_pk_fma_f32 v[54:55], v[56:57], v[54:55], v[94:95]
	v_pk_fma_f32 v[52:53], v[58:59], v[52:53], v[92:93]
	v_bfe_u32 v58, v54, 16, 1
	v_bfe_u32 v56, v52, 16, 1
	v_bfe_u32 v57, v53, 16, 1
	v_bfe_u32 v59, v55, 16, 1
	v_add3_u32 v52, v52, v56, s61
	v_add3_u32 v54, v54, v58, s61
	v_add3_u32 v53, v53, v57, s61
	v_add3_u32 v55, v55, v59, s61
	v_lshrrev_b32_e32 v52, 16, v52
	v_lshrrev_b32_e32 v54, 16, v54
	v_and_or_b32 v52, v53, s86, v52
	v_and_or_b32 v53, v55, s86, v54
	global_store_dwordx2 v[74:75], v[52:53], off offset:1024
	global_load_dwordx4 v[52:55], v[64:65], off offset:3072
	s_nop 0
	global_load_dwordx4 v[56:59], v87, s[10:11]
	global_load_dwordx4 v[60:63], v84, s[8:9] offset:3072
	s_waitcnt vmcnt(2)
	v_pk_mul_f32 v[44:45], v[52:53], v[44:45]
	v_pk_mul_f32 v[46:47], v[54:55], v[46:47]
	s_waitcnt vmcnt(1)
	v_pk_add_f32 v[52:53], v[58:59], 1.0 op_sel_hi:[1,0]
	v_pk_add_f32 v[54:55], v[56:57], 1.0 op_sel_hi:[1,0]
	s_waitcnt vmcnt(0)
	v_pk_fma_f32 v[46:47], v[52:53], v[46:47], v[62:63]
	v_pk_fma_f32 v[44:45], v[54:55], v[44:45], v[60:61]
	v_bfe_u32 v54, v46, 16, 1
	v_bfe_u32 v52, v44, 16, 1
	v_bfe_u32 v53, v45, 16, 1
	v_bfe_u32 v55, v47, 16, 1
	v_add3_u32 v44, v44, v52, s61
	v_add3_u32 v46, v46, v54, s61
	v_add3_u32 v45, v45, v53, s61
	v_add3_u32 v47, v47, v55, s61
	v_lshrrev_b32_e32 v44, 16, v44
	v_lshrrev_b32_e32 v46, 16, v46
	v_and_or_b32 v44, v45, s86, v44
	v_and_or_b32 v45, v47, s86, v46
	global_store_dwordx2 v[74:75], v[44:45], off offset:1536
	global_load_dwordx4 v[44:47], v[66:67], off
	s_nop 0
	global_load_dwordx4 v[52:55], v88, s[10:11]
	global_load_dwordx4 v[56:59], v88, s[8:9]
	s_waitcnt vmcnt(2)
	v_pk_mul_f32 v[40:41], v[44:45], v[40:41]
	v_pk_mul_f32 v[42:43], v[46:47], v[42:43]
	s_waitcnt vmcnt(1)
	v_pk_add_f32 v[44:45], v[54:55], 1.0 op_sel_hi:[1,0]
	v_pk_add_f32 v[46:47], v[52:53], 1.0 op_sel_hi:[1,0]
	s_waitcnt vmcnt(0)
	v_pk_fma_f32 v[42:43], v[42:43], v[44:45], v[58:59]
	v_pk_fma_f32 v[40:41], v[40:41], v[46:47], v[56:57]
	v_bfe_u32 v46, v42, 16, 1
	v_bfe_u32 v44, v40, 16, 1
	v_bfe_u32 v45, v41, 16, 1
	v_bfe_u32 v47, v43, 16, 1
	v_add3_u32 v40, v40, v44, s61
	v_add3_u32 v42, v42, v46, s61
	v_add3_u32 v41, v41, v45, s61
	v_add3_u32 v43, v43, v47, s61
	v_lshrrev_b32_e32 v40, 16, v40
	v_lshrrev_b32_e32 v42, 16, v42
	v_and_or_b32 v40, v41, s86, v40
	v_and_or_b32 v41, v43, s86, v42
	global_store_dwordx2 v[74:75], v[40:41], off offset:2048
	global_load_dwordx4 v[40:43], v[68:69], off
	s_nop 0
	global_load_dwordx4 v[44:47], v89, s[10:11]
	global_load_dwordx4 v[52:55], v89, s[8:9]
	v_mov_b64_e32 v[58:59], v[26:27]
	v_mov_b64_e32 v[56:57], v[24:25]
	s_waitcnt vmcnt(2)
	v_pk_mul_f32 v[36:37], v[36:37], v[40:41]
	v_pk_mul_f32 v[38:39], v[38:39], v[42:43]
	s_waitcnt vmcnt(1)
	v_pk_add_f32 v[40:41], v[46:47], 1.0 op_sel_hi:[1,0]
	v_pk_add_f32 v[42:43], v[44:45], 1.0 op_sel_hi:[1,0]
	s_waitcnt vmcnt(0)
	v_pk_fma_f32 v[38:39], v[38:39], v[40:41], v[54:55]
	v_pk_fma_f32 v[36:37], v[36:37], v[42:43], v[52:53]
	v_bfe_u32 v42, v38, 16, 1
	v_bfe_u32 v40, v36, 16, 1
	v_bfe_u32 v41, v37, 16, 1
	v_bfe_u32 v43, v39, 16, 1
	v_add3_u32 v36, v36, v40, s61
	v_add3_u32 v38, v38, v42, s61
	v_add3_u32 v37, v37, v41, s61
	v_add3_u32 v39, v39, v43, s61
	v_lshrrev_b32_e32 v36, 16, v36
	v_lshrrev_b32_e32 v38, 16, v38
	v_and_or_b32 v36, v37, s86, v36
	v_and_or_b32 v37, v39, s86, v38
	global_store_dwordx2 v[74:75], v[36:37], off offset:2560
	global_load_dwordx4 v[36:39], v[70:71], off
	s_nop 0
	global_load_dwordx4 v[40:43], v90, s[10:11]
	global_load_dwordx4 v[44:47], v90, s[8:9]
	v_mov_b64_e32 v[54:55], v[22:23]
	v_mov_b64_e32 v[52:53], v[20:21]
	s_waitcnt vmcnt(2)
	v_pk_mul_f32 v[32:33], v[32:33], v[36:37]
	v_pk_mul_f32 v[34:35], v[34:35], v[38:39]
	s_waitcnt vmcnt(1)
	v_pk_add_f32 v[36:37], v[42:43], 1.0 op_sel_hi:[1,0]
	v_pk_add_f32 v[38:39], v[40:41], 1.0 op_sel_hi:[1,0]
	s_waitcnt vmcnt(0)
	v_pk_fma_f32 v[34:35], v[34:35], v[36:37], v[46:47]
	v_pk_fma_f32 v[32:33], v[32:33], v[38:39], v[44:45]
	v_bfe_u32 v38, v34, 16, 1
	v_bfe_u32 v36, v32, 16, 1
	v_bfe_u32 v37, v33, 16, 1
	v_bfe_u32 v39, v35, 16, 1
	v_add3_u32 v32, v32, v36, s61
	v_add3_u32 v34, v34, v38, s61
	v_add3_u32 v33, v33, v37, s61
	v_add3_u32 v35, v35, v39, s61
	v_lshrrev_b32_e32 v32, 16, v32
	v_lshrrev_b32_e32 v34, 16, v34
	v_and_or_b32 v32, v33, s86, v32
	v_and_or_b32 v33, v35, s86, v34
	global_store_dwordx2 v[74:75], v[32:33], off offset:3072
	global_load_dwordx4 v[60:63], v[72:73], off
	global_load_dwordx4 v[92:95], v91, s[10:11]
	global_load_dwordx4 v[96:99], v91, s[8:9]
	v_mov_b64_e32 v[34:35], v[6:7]
	v_mov_b64_e32 v[38:39], v[10:11]
	v_mov_b64_e32 v[42:43], v[14:15]
	v_mov_b64_e32 v[46:47], v[18:19]
	v_mov_b64_e32 v[32:33], v[4:5]
	v_mov_b64_e32 v[36:37], v[8:9]
	v_mov_b64_e32 v[40:41], v[12:13]
	v_mov_b64_e32 v[44:45], v[16:17]
	s_waitcnt vmcnt(2)
	v_pk_mul_f32 v[60:61], v[76:77], v[60:61]
	v_pk_mul_f32 v[62:63], v[100:101], v[62:63]
	s_waitcnt vmcnt(1)
	v_pk_add_f32 v[76:77], v[94:95], 1.0 op_sel_hi:[1,0]
	v_pk_add_f32 v[92:93], v[92:93], 1.0 op_sel_hi:[1,0]
	s_waitcnt vmcnt(0)
	v_pk_fma_f32 v[62:63], v[62:63], v[76:77], v[98:99]
	v_pk_fma_f32 v[60:61], v[60:61], v[92:93], v[96:97]
	v_bfe_u32 v92, v62, 16, 1
	v_bfe_u32 v76, v60, 16, 1
	v_bfe_u32 v77, v61, 16, 1
	v_bfe_u32 v93, v63, 16, 1
	v_add3_u32 v60, v60, v76, s61
	v_add3_u32 v62, v62, v92, s61
	v_add3_u32 v61, v61, v77, s61
	v_add3_u32 v63, v63, v93, s61
	v_lshrrev_b32_e32 v60, 16, v60
	v_lshrrev_b32_e32 v62, 16, v62
	v_and_or_b32 v60, v61, s86, v60
	v_and_or_b32 v61, v63, s86, v62
	global_store_dwordx2 v[74:75], v[60:61], off offset:3584
	v_mov_b64_e32 v[62:63], v[30:31]
	v_lshl_add_u64 v[74:75], v[74:75], 0, s[4:5]
	v_mov_b64_e32 v[60:61], v[28:29]
	s_cbranch_vccz .LBB0_1389
